# attention-phase prologue: the 8-iteration gain-max loop unrolled with all 32 loads issued before one wait
# baseline (speedup 1.0000x reference)
; #define LAS __attribute__((address_space(3)))
; __device__ __forceinline__ void attn_unit(const bf16_t* Q, const bf16_t* K, const bf16_t* Vt, int ntiles, int nrows, bf16_t* O, float negM, LAS unsigned char* lds, int tid) {
;     const int lane = tid & 63, w = tid >> 6, r32 = lane & 31, hi = lane >> 5;
;     const int row0 = w * 64 + r32, row1 = row0 + 32;
;     bf16x8 qa[4], qb[4];
;     {
;         const bf16_t* qp0 = Q + (size_t)min(row0, nrows - 1) * 64 + hi * 8;
;         const bf16_t* qp1 = Q + (size_t)min(row1, nrows - 1) * 64 + hi * 8;
; #pragma unroll
;         for (int s = 0; s < 4; ++s) { qa[s] = *(const bf16x8*)(qp0 + 16 * s); qb[s] = *(const bf16x8*)(qp1 + 16 * s); }
;     }
;     LAS unsigned char* qlds = lds + 40960 + w * 4096 + lane * 16;
; #pragma unroll
;     for (int s = 0; s < 4; ++s) *(LAS bf16x8*)(qlds + s * 1024) = qb[s];
;     f32x16 oa0, oa1, ob0, ob1;
; #pragma unroll
;     for (int e = 0; e < 16; ++e) { oa0[e] = 0.f; oa1[e] = 0.f; ob0[e] = 0.f; ob1[e] = 0.f; }
;     float lsa = 0.f, lsb = 0.f;
;     const int srow = tid >> 3, sch = tid & 7;
;     const bf16_t* kg = K + srow * 64 + sch * 8;
;     const bf16_t* vg = Vt + (size_t)srow * TKV + sch * 8;
;     const int soff = srow * 144 + sch * 16;
;     u32x4 kr = *(const u32x4*)kg, vr = *(const u32x4*)vg;
;     *(LAS u32x4*)(lds + soff) = kr; *(LAS u32x4*)(lds + 9216 + soff) = vr;
;     __syncthreads();
;     const int foff = r32 * 144 + hi * 16;
; __device__ __forceinline__ void attn_phase(const Params& p, int l, LAS unsigned char* lds, int tid) {
;     ...
;     float mq = 0.f, mk = 0.f;
;     for (int i = 0; i < 64; ++i) { mq = fmaxf(mq, fabsf(p.qg[l * 64 + i])); mk = fmaxf(mk, fabsf(p.kg[l * 64 + i])); }
;     const float negM = -(8.0f * 1.4426950408889634f) * mq * mk * 1.02f - 0.25f;
.LBB0_474:
	s_mov_b32 s10, s7
	s_mov_b32 s11, s8
	global_load_dwordx4 v[2:5], v187, s[4:5] offset:16
	global_load_dwordx4 v[6:9], v187, s[4:5]
	global_load_dwordx4 v[10:13], v187, s[10:11]
	global_load_dwordx4 v[14:17], v187, s[10:11] offset:16
	global_load_dwordx4 v[18:21], v187, s[4:5] offset:48
	global_load_dwordx4 v[22:25], v187, s[4:5] offset:32
	global_load_dwordx4 v[26:29], v187, s[10:11] offset:32
	global_load_dwordx4 v[30:33], v187, s[10:11] offset:48
	global_load_dwordx4 v[34:37], v187, s[4:5] offset:80
	global_load_dwordx4 v[38:41], v187, s[4:5] offset:64
	global_load_dwordx4 v[42:45], v187, s[10:11] offset:64
	global_load_dwordx4 v[46:49], v187, s[10:11] offset:80
	global_load_dwordx4 v[50:53], v187, s[4:5] offset:112
	global_load_dwordx4 v[54:57], v187, s[4:5] offset:96
	global_load_dwordx4 v[58:61], v187, s[10:11] offset:96
	global_load_dwordx4 v[62:65], v187, s[10:11] offset:112
	global_load_dwordx4 v[66:69], v187, s[4:5] offset:144
	global_load_dwordx4 v[70:73], v187, s[4:5] offset:128
	global_load_dwordx4 v[74:77], v187, s[10:11] offset:128
	global_load_dwordx4 v[78:81], v187, s[10:11] offset:144
	global_load_dwordx4 v[82:85], v187, s[4:5] offset:176
	global_load_dwordx4 v[86:89], v187, s[4:5] offset:160
	global_load_dwordx4 v[90:93], v187, s[10:11] offset:160
	global_load_dwordx4 v[94:97], v187, s[10:11] offset:176
	global_load_dwordx4 v[98:101], v187, s[4:5] offset:208
	global_load_dwordx4 v[102:105], v187, s[4:5] offset:192
	global_load_dwordx4 v[106:109], v187, s[10:11] offset:192
	global_load_dwordx4 v[110:113], v187, s[10:11] offset:208
	global_load_dwordx4 v[114:117], v187, s[4:5] offset:240
	global_load_dwordx4 v[118:121], v187, s[4:5] offset:224
	global_load_dwordx4 v[122:125], v187, s[10:11] offset:224
	global_load_dwordx4 v[126:129], v187, s[10:11] offset:240
	s_waitcnt vmcnt(0)
	v_max3_f32 v1, v1, |v6|, |v7|
	v_max3_f32 v1, v1, |v8|, |v9|
	v_max3_f32 v0, v0, |v10|, |v11|
	v_max3_f32 v0, v0, |v12|, |v13|
	v_max3_f32 v1, v1, |v2|, |v3|
	v_max3_f32 v0, v0, |v14|, |v15|
	v_max3_f32 v1, v1, |v4|, |v5|
	v_max3_f32 v0, v0, |v16|, |v17|
	v_max3_f32 v1, v1, |v22|, |v23|
	v_max3_f32 v1, v1, |v24|, |v25|
	v_max3_f32 v0, v0, |v26|, |v27|
	v_max3_f32 v0, v0, |v28|, |v29|
	v_max3_f32 v1, v1, |v18|, |v19|
	v_max3_f32 v0, v0, |v30|, |v31|
	v_max3_f32 v1, v1, |v20|, |v21|
	v_max3_f32 v0, v0, |v32|, |v33|
	v_max3_f32 v1, v1, |v38|, |v39|
	v_max3_f32 v1, v1, |v40|, |v41|
	v_max3_f32 v0, v0, |v42|, |v43|
	v_max3_f32 v0, v0, |v44|, |v45|
	v_max3_f32 v1, v1, |v34|, |v35|
	v_max3_f32 v0, v0, |v46|, |v47|
	v_max3_f32 v1, v1, |v36|, |v37|
	v_max3_f32 v0, v0, |v48|, |v49|
	v_max3_f32 v1, v1, |v54|, |v55|
	v_max3_f32 v1, v1, |v56|, |v57|
	v_max3_f32 v0, v0, |v58|, |v59|
	v_max3_f32 v0, v0, |v60|, |v61|
	v_max3_f32 v1, v1, |v50|, |v51|
	v_max3_f32 v0, v0, |v62|, |v63|
	v_max3_f32 v1, v1, |v52|, |v53|
	v_max3_f32 v0, v0, |v64|, |v65|
	v_max3_f32 v1, v1, |v70|, |v71|
	v_max3_f32 v1, v1, |v72|, |v73|
	v_max3_f32 v0, v0, |v74|, |v75|
	v_max3_f32 v0, v0, |v76|, |v77|
	v_max3_f32 v1, v1, |v66|, |v67|
	v_max3_f32 v0, v0, |v78|, |v79|
	v_max3_f32 v1, v1, |v68|, |v69|
	v_max3_f32 v0, v0, |v80|, |v81|
	v_max3_f32 v1, v1, |v86|, |v87|
	v_max3_f32 v1, v1, |v88|, |v89|
	v_max3_f32 v0, v0, |v90|, |v91|
	v_max3_f32 v0, v0, |v92|, |v93|
	v_max3_f32 v1, v1, |v82|, |v83|
	v_max3_f32 v0, v0, |v94|, |v95|
	v_max3_f32 v1, v1, |v84|, |v85|
	v_max3_f32 v0, v0, |v96|, |v97|
	v_max3_f32 v1, v1, |v102|, |v103|
	v_max3_f32 v1, v1, |v104|, |v105|
	v_max3_f32 v0, v0, |v106|, |v107|
	v_max3_f32 v0, v0, |v108|, |v109|
	v_max3_f32 v1, v1, |v98|, |v99|
	v_max3_f32 v0, v0, |v110|, |v111|
	v_max3_f32 v1, v1, |v100|, |v101|
	v_max3_f32 v0, v0, |v112|, |v113|
	v_max3_f32 v1, v1, |v118|, |v119|
	v_max3_f32 v1, v1, |v120|, |v121|
	v_max3_f32 v0, v0, |v122|, |v123|
	v_max3_f32 v0, v0, |v124|, |v125|
	v_max3_f32 v1, v1, |v114|, |v115|
	v_max3_f32 v0, v0, |v126|, |v127|
	v_max3_f32 v1, v1, |v116|, |v117|
	v_max3_f32 v0, v0, |v128|, |v129|
	s_cmp_ge_i32 s2, s6
	s_cbranch_scc1 .LBB0_491
	v_lshlrev_b32_e32 v2, 6, v144
	v_and_b32_e32 v2, 0xfffff000, v2
	v_ashrrev_i32_e32 v4, 3, v144
	v_add_u32_e32 v22, 0, v2
	v_lshlrev_b32_e32 v2, 6, v4
	v_ashrrev_i32_e32 v3, 31, v2
	v_readlane_b32 s0, v255, 1
	v_lshlrev_b64 v[18:19], 1, v[2:3]
	v_readlane_b32 s1, v255, 2
	s_movk_i32 s4, 0x2200
	v_lshlrev_b32_e32 v5, 4, v144
	v_lshl_add_u64 v[2:3], s[0:1], 0, v[18:19]
	v_mad_i64_i32 v[20:21], s[0:1], v4, s4, 0
	v_readlane_b32 s0, v254, 48
	v_and_b32_e32 v186, 0x70, v5
	v_readlane_b32 s1, v254, 49
	v_lshl_add_u64 v[174:175], v[2:3], 0, v[186:187]
	v_mul_f32_e32 v1, 0xc138aa3b, v1
	v_mov_b64_e32 v[2:3], s[0:1]
	v_mad_i64_i32 v[2:3], s[0:1], v4, s4, v[2:3]
	s_movk_i32 s0, 0x90
	v_mul_f32_e32 v0, v0, v1
	v_mov_b32_e32 v1, 0xbe800000
	v_lshl_add_u64 v[176:177], v[2:3], 0, v[186:187]
	v_mul_lo_u32 v2, v4, s0
	v_readlane_b32 s0, v253, 2
	v_fmamk_f32 v0, v0, 0x3f828f5c, v1
	v_and_b32_e32 v1, 63, v144
	v_or_b32_e32 v20, v20, v186
	v_readlane_b32 s1, v253, 3
	v_bfe_u32 v17, v144, 5, 1
	v_and_b32_e32 v170, 0xffffffdf, v144
	v_or_b32_e32 v172, 32, v144
	v_lshlrev_b32_e32 v23, 4, v1
	v_and_b32_e32 v1, 31, v144
	v_lshl_add_u64 v[184:185], s[0:1], 0, v[20:21]
	v_readlane_b32 s0, v253, 4
	v_lshlrev_b32_e32 v16, 3, v17
	v_add3_u32 v145, v2, v186, 0
	v_mul_u32_u24_e32 v1, 0x90, v1
	v_lshlrev_b32_e32 v2, 4, v17
	v_ashrrev_i32_e32 v171, 31, v170
	v_ashrrev_i32_e32 v173, 31, v172
	v_or_b32_e32 v18, v18, v186
	v_readlane_b32 s1, v253, 5
	v_add3_u32 v181, 0, v1, v2
	v_mov_b32_e32 v1, v0
	v_mov_b32_e32 v2, v0
	v_mov_b32_e32 v3, v0
	v_mov_b32_e32 v4, v0
	v_mov_b32_e32 v5, v0
	v_mov_b32_e32 v6, v0
	v_mov_b32_e32 v7, v0
	v_mov_b32_e32 v8, v0
	v_mov_b32_e32 v9, v0
	v_mov_b32_e32 v10, v0
	v_mov_b32_e32 v11, v0
	v_mov_b32_e32 v12, v0
	v_mov_b32_e32 v13, v0
	v_mov_b32_e32 v14, v0
	v_mov_b32_e32 v15, v0
	v_lshlrev_b64 v[178:179], 11, v[170:171]
	v_lshlrev_b32_e32 v180, 2, v17
	v_lshlrev_b64 v[182:183], 11, v[172:173]
	v_lshl_add_u64 v[192:193], s[0:1], 0, v[18:19]
	v_lshlrev_b32_e32 v186, 1, v16
	v_add_u32_e32 v171, v22, v23
	s_mov_b32 s7, s2
	s_branch .LBB0_478
